# adds to v71: gate pre-activation tail loads (sum-of-squares, gate bias) issued at the top of each row-pair iteration instead of after the reduction
# speedup vs baseline: 1.0017x; 1.0017x over previous
; #define LAS __attribute__((address_space(3)))
; DI float frsq(float x) { return __builtin_amdgcn_rsqf(x); }
; DI float ss_get(const ss_t* ss, int r) { return (float)ss[r] * (1.0f / 1048576.0f); }
; DI void gates_phase(LAS unsigned char* lds, const bf16_t* X, const ss_t* ss, const float* win  , const float* ng, const float* gbias, float* GATES, int G, int bid) {
;     ...
;     for (int m0 = gw; m0 < T_ALL; m0 += 2 * NGW) {
;         float acc[2][8];
; #pragma unroll
;         for (int r = 0; r < 2; ++r)
; #pragma unroll
;             for (int j = 0; j < 8; ++j) acc[r][j] = 0.f;
;         const bf16_t* xr0 = X + (size_t)m0 * 1024; const bf16_t* xr1 = X + (size_t)(m0 + NGW) * 1024;
; #pragma unroll 4
;         for (int i = 0; i < 16; ++i) { const int k = lane + 64 * i; const float x0 = __builtin_bit_cast(float, (unsigned)xr0[k] << 16), x1 = __builtin_bit_cast(float, (unsigned)xr1[k] << 16); const f32x4 a = *(const LAS f32x4*)(wg + k * 8), b = *(const LAS f32x4*)(wg + k * 8 + 4);
; #pragma unroll
;             for (int e = 0; e < 4; ++e) { acc[0][e] += x0 * a[e]; acc[0][4 + e] += x0 * b[e]; acc[1][e] += x1 * a[e]; acc[1][4 + e] += x1 * b[e]; } }
;     ...
;             const float rs = frsq(ss_get(ss, m) * (1.0f / 1024.0f) + EPS);
;             if (lane < 8) { const int j = (lane & 1) * 4 + ((lane >> 1) & 1) * 2 + ((lane >> 2) & 1);
;                 float v = v1 * rs + gbias[j];
.LBB0_446:
	v_mov_b32_e32 v84, v0
	v_ashrrev_i32_e32 v85, 31, v0
	v_add_u32_e32 v86, s33, v0
	v_lshl_add_u64 v[84:85], v[84:85], 3, s[48:49]
	v_ashrrev_i32_e32 v87, 31, v86
	global_load_dwordx2 v[84:85], v[84:85], off
	v_lshl_add_u64 v[86:87], v[86:87], 3, s[48:49]
	global_load_dword v88, v[2:3], off
	global_load_dwordx2 v[86:87], v[86:87], off
	global_load_ushort v52, v[8:9], off offset:-256
	global_load_ushort v53, v[6:7], off offset:-256
	global_load_ushort v54, v[8:9], off offset:-128
	global_load_ushort v55, v[6:7], off offset:-128
	global_load_ushort v56, v[8:9], off
	global_load_ushort v57, v[6:7], off
	global_load_ushort v58, v[8:9], off offset:128
	global_load_ushort v59, v[6:7], off offset:128
	global_load_ushort v60, v[8:9], off offset:256
	global_load_ushort v61, v[6:7], off offset:256
	global_load_ushort v62, v[8:9], off offset:384
	global_load_ushort v63, v[6:7], off offset:384
	global_load_ushort v64, v[8:9], off offset:512
	global_load_ushort v65, v[6:7], off offset:512
	global_load_ushort v66, v[8:9], off offset:640
	global_load_ushort v67, v[6:7], off offset:640
	global_load_ushort v68, v[8:9], off offset:768
	global_load_ushort v69, v[6:7], off offset:768
	global_load_ushort v70, v[8:9], off offset:896
	global_load_ushort v71, v[6:7], off offset:896
	global_load_ushort v72, v[8:9], off offset:1024
	global_load_ushort v73, v[6:7], off offset:1024
	global_load_ushort v74, v[8:9], off offset:1152
	global_load_ushort v75, v[6:7], off offset:1152
	global_load_ushort v76, v[8:9], off offset:1280
	global_load_ushort v77, v[6:7], off offset:1280
	global_load_ushort v78, v[8:9], off offset:1408
	global_load_ushort v79, v[6:7], off offset:1408
	global_load_ushort v80, v[8:9], off offset:1536
	global_load_ushort v81, v[6:7], off offset:1536
	global_load_ushort v82, v[8:9], off offset:1664
	global_load_ushort v83, v[6:7], off offset:1664
	s_waitcnt vmcnt(31)
	v_lshlrev_b32_e32 v44, 16, v52
	ds_read_b128 v[34:37], v1
	ds_read_b128 v[38:41], v1 offset:16
	s_waitcnt lgkmcnt(1)
	v_pk_fma_f32 v[18:19], v[36:37], v[44:45], v[18:19] op_sel_hi:[1,0,1]
	v_pk_fma_f32 v[22:23], v[34:35], v[44:45], v[22:23] op_sel_hi:[1,0,1]
	s_waitcnt lgkmcnt(0)
	v_pk_fma_f32 v[24:25], v[38:39], v[44:45], v[24:25] op_sel_hi:[1,0,1]
	v_pk_fma_f32 v[20:21], v[40:41], v[44:45], v[20:21] op_sel_hi:[1,0,1]
	s_waitcnt vmcnt(30)
	v_lshlrev_b32_e32 v48, 16, v53
	v_pk_fma_f32 v[36:37], v[36:37], v[48:49], v[10:11] op_sel_hi:[1,0,1]
	v_pk_fma_f32 v[34:35], v[34:35], v[48:49], v[14:15] op_sel_hi:[1,0,1]
	v_pk_fma_f32 v[38:39], v[38:39], v[48:49], v[16:17] op_sel_hi:[1,0,1]
	v_pk_fma_f32 v[40:41], v[40:41], v[48:49], v[12:13] op_sel_hi:[1,0,1]
	s_waitcnt vmcnt(29)
	v_lshlrev_b32_e32 v44, 16, v54
	s_waitcnt vmcnt(28)
	v_lshlrev_b32_e32 v48, 16, v55
	ds_read_b128 v[10:13], v1 offset:2048
	ds_read_b128 v[14:17], v1 offset:2064
	s_waitcnt lgkmcnt(1)
	v_pk_fma_f32 v[22:23], v[10:11], v[44:45], v[22:23] op_sel_hi:[1,0,1]
	v_pk_fma_f32 v[34:35], v[10:11], v[48:49], v[34:35] op_sel_hi:[1,0,1]
	s_waitcnt lgkmcnt(0)
	v_pk_fma_f32 v[24:25], v[14:15], v[44:45], v[24:25] op_sel_hi:[1,0,1]
	v_pk_fma_f32 v[18:19], v[12:13], v[44:45], v[18:19] op_sel_hi:[1,0,1]
	v_pk_fma_f32 v[20:21], v[16:17], v[44:45], v[20:21] op_sel_hi:[1,0,1]
	v_pk_fma_f32 v[38:39], v[14:15], v[48:49], v[38:39] op_sel_hi:[1,0,1]
	v_pk_fma_f32 v[36:37], v[12:13], v[48:49], v[36:37] op_sel_hi:[1,0,1]
	v_pk_fma_f32 v[40:41], v[16:17], v[48:49], v[40:41] op_sel_hi:[1,0,1]
	s_waitcnt vmcnt(27)
	v_lshlrev_b32_e32 v44, 16, v56
	s_waitcnt vmcnt(26)
	v_lshlrev_b32_e32 v48, 16, v57
	ds_read_b128 v[10:13], v1 offset:4096
	ds_read_b128 v[14:17], v1 offset:4112
	s_waitcnt lgkmcnt(1)
	v_pk_fma_f32 v[22:23], v[10:11], v[44:45], v[22:23] op_sel_hi:[1,0,1]
	v_pk_fma_f32 v[50:51], v[10:11], v[48:49], v[34:35] op_sel_hi:[1,0,1]
	s_waitcnt lgkmcnt(0)
	v_pk_fma_f32 v[24:25], v[14:15], v[44:45], v[24:25] op_sel_hi:[1,0,1]
	v_pk_fma_f32 v[18:19], v[12:13], v[44:45], v[18:19] op_sel_hi:[1,0,1]
	v_pk_fma_f32 v[20:21], v[16:17], v[44:45], v[20:21] op_sel_hi:[1,0,1]
	v_pk_fma_f32 v[44:45], v[12:13], v[48:49], v[36:37] op_sel_hi:[1,0,1]
	v_pk_fma_f32 v[38:39], v[14:15], v[48:49], v[38:39] op_sel_hi:[1,0,1]
	v_pk_fma_f32 v[40:41], v[16:17], v[48:49], v[40:41] op_sel_hi:[1,0,1]
	s_waitcnt vmcnt(25)
	v_lshlrev_b32_e32 v42, 16, v58
	s_waitcnt vmcnt(24)
	v_lshlrev_b32_e32 v46, 16, v59
	ds_read_b128 v[10:13], v1 offset:6144
	ds_read_b128 v[34:37], v1 offset:6160
	s_waitcnt lgkmcnt(1)
	v_pk_fma_f32 v[22:23], v[10:11], v[42:43], v[22:23] op_sel_hi:[1,0,1]
	s_waitcnt lgkmcnt(0)
	v_pk_fma_f32 v[24:25], v[34:35], v[42:43], v[24:25] op_sel_hi:[1,0,1]
	v_pk_fma_f32 v[14:15], v[10:11], v[46:47], v[50:51] op_sel_hi:[1,0,1]
	v_pk_fma_f32 v[16:17], v[34:35], v[46:47], v[38:39] op_sel_hi:[1,0,1]
	v_pk_fma_f32 v[18:19], v[12:13], v[42:43], v[18:19] op_sel_hi:[1,0,1]
	v_pk_fma_f32 v[20:21], v[36:37], v[42:43], v[20:21] op_sel_hi:[1,0,1]
	v_pk_fma_f32 v[10:11], v[12:13], v[46:47], v[44:45] op_sel_hi:[1,0,1]
	v_pk_fma_f32 v[12:13], v[36:37], v[46:47], v[40:41] op_sel_hi:[1,0,1]
	s_waitcnt vmcnt(23)
	v_lshlrev_b32_e32 v44, 16, v60
	ds_read_b128 v[34:37], v1 offset:8192
	ds_read_b128 v[38:41], v1 offset:8208
	s_waitcnt lgkmcnt(1)
	v_pk_fma_f32 v[18:19], v[36:37], v[44:45], v[18:19] op_sel_hi:[1,0,1]
	v_pk_fma_f32 v[22:23], v[34:35], v[44:45], v[22:23] op_sel_hi:[1,0,1]
	s_waitcnt lgkmcnt(0)
	v_pk_fma_f32 v[24:25], v[38:39], v[44:45], v[24:25] op_sel_hi:[1,0,1]
	v_pk_fma_f32 v[20:21], v[40:41], v[44:45], v[20:21] op_sel_hi:[1,0,1]
	s_waitcnt vmcnt(22)
; #define LAS __attribute__((address_space(3)))
; DI void gates_phase(LAS unsigned char* lds, const bf16_t* X, const ss_t* ss, const float* win  , const float* ng, const float* gbias, float* GATES, int G, int bid) {
;     ...
; #pragma unroll 4
;         for (int i = 0; i < 16; ++i) { const int k = lane + 64 * i; const float x0 = __builtin_bit_cast(float, (unsigned)xr0[k] << 16), x1 = __builtin_bit_cast(float, (unsigned)xr1[k] << 16); const f32x4 a = *(const LAS f32x4*)(wg + k * 8), b = *(const LAS f32x4*)(wg + k * 8 + 4);
; #pragma unroll
;             for (int e = 0; e < 4; ++e) { acc[0][e] += x0 * a[e]; acc[0][4 + e] += x0 * b[e]; acc[1][e] += x1 * a[e]; acc[1][4 + e] += x1 * b[e]; } }
	v_lshlrev_b32_e32 v48, 16, v61
	v_pk_fma_f32 v[36:37], v[36:37], v[48:49], v[10:11] op_sel_hi:[1,0,1]
	v_pk_fma_f32 v[34:35], v[34:35], v[48:49], v[14:15] op_sel_hi:[1,0,1]
	v_pk_fma_f32 v[38:39], v[38:39], v[48:49], v[16:17] op_sel_hi:[1,0,1]
	v_pk_fma_f32 v[40:41], v[40:41], v[48:49], v[12:13] op_sel_hi:[1,0,1]
	s_waitcnt vmcnt(21)
	v_lshlrev_b32_e32 v44, 16, v62
	s_waitcnt vmcnt(20)
	v_lshlrev_b32_e32 v48, 16, v63
	ds_read_b128 v[10:13], v1 offset:10240
	ds_read_b128 v[14:17], v1 offset:10256
	s_waitcnt lgkmcnt(1)
	v_pk_fma_f32 v[22:23], v[10:11], v[44:45], v[22:23] op_sel_hi:[1,0,1]
	v_pk_fma_f32 v[34:35], v[10:11], v[48:49], v[34:35] op_sel_hi:[1,0,1]
	s_waitcnt lgkmcnt(0)
	v_pk_fma_f32 v[24:25], v[14:15], v[44:45], v[24:25] op_sel_hi:[1,0,1]
	v_pk_fma_f32 v[18:19], v[12:13], v[44:45], v[18:19] op_sel_hi:[1,0,1]
	v_pk_fma_f32 v[20:21], v[16:17], v[44:45], v[20:21] op_sel_hi:[1,0,1]
	v_pk_fma_f32 v[38:39], v[14:15], v[48:49], v[38:39] op_sel_hi:[1,0,1]
	v_pk_fma_f32 v[36:37], v[12:13], v[48:49], v[36:37] op_sel_hi:[1,0,1]
	v_pk_fma_f32 v[40:41], v[16:17], v[48:49], v[40:41] op_sel_hi:[1,0,1]
	s_waitcnt vmcnt(19)
	v_lshlrev_b32_e32 v44, 16, v64
	s_waitcnt vmcnt(18)
	v_lshlrev_b32_e32 v48, 16, v65
	ds_read_b128 v[10:13], v1 offset:12288
	ds_read_b128 v[14:17], v1 offset:12304
	s_waitcnt lgkmcnt(1)
	v_pk_fma_f32 v[22:23], v[10:11], v[44:45], v[22:23] op_sel_hi:[1,0,1]
	v_pk_fma_f32 v[50:51], v[10:11], v[48:49], v[34:35] op_sel_hi:[1,0,1]
	s_waitcnt lgkmcnt(0)
	v_pk_fma_f32 v[24:25], v[14:15], v[44:45], v[24:25] op_sel_hi:[1,0,1]
	v_pk_fma_f32 v[18:19], v[12:13], v[44:45], v[18:19] op_sel_hi:[1,0,1]
	v_pk_fma_f32 v[20:21], v[16:17], v[44:45], v[20:21] op_sel_hi:[1,0,1]
	v_pk_fma_f32 v[44:45], v[12:13], v[48:49], v[36:37] op_sel_hi:[1,0,1]
	v_pk_fma_f32 v[38:39], v[14:15], v[48:49], v[38:39] op_sel_hi:[1,0,1]
	v_pk_fma_f32 v[40:41], v[16:17], v[48:49], v[40:41] op_sel_hi:[1,0,1]
	s_waitcnt vmcnt(17)
	v_lshlrev_b32_e32 v42, 16, v66
	s_waitcnt vmcnt(16)
	v_lshlrev_b32_e32 v46, 16, v67
	ds_read_b128 v[10:13], v1 offset:14336
	ds_read_b128 v[34:37], v1 offset:14352
	s_waitcnt lgkmcnt(1)
	v_pk_fma_f32 v[22:23], v[10:11], v[42:43], v[22:23] op_sel_hi:[1,0,1]
	s_waitcnt lgkmcnt(0)
	v_pk_fma_f32 v[24:25], v[34:35], v[42:43], v[24:25] op_sel_hi:[1,0,1]
	v_pk_fma_f32 v[14:15], v[10:11], v[46:47], v[50:51] op_sel_hi:[1,0,1]
	v_pk_fma_f32 v[16:17], v[34:35], v[46:47], v[38:39] op_sel_hi:[1,0,1]
	v_pk_fma_f32 v[18:19], v[12:13], v[42:43], v[18:19] op_sel_hi:[1,0,1]
	v_pk_fma_f32 v[20:21], v[36:37], v[42:43], v[20:21] op_sel_hi:[1,0,1]
	v_pk_fma_f32 v[10:11], v[12:13], v[46:47], v[44:45] op_sel_hi:[1,0,1]
	v_pk_fma_f32 v[12:13], v[36:37], v[46:47], v[40:41] op_sel_hi:[1,0,1]
	s_waitcnt vmcnt(15)
	v_lshlrev_b32_e32 v44, 16, v68
	ds_read_b128 v[34:37], v1 offset:16384
	ds_read_b128 v[38:41], v1 offset:16400
	s_waitcnt lgkmcnt(1)
	v_pk_fma_f32 v[18:19], v[36:37], v[44:45], v[18:19] op_sel_hi:[1,0,1]
	v_pk_fma_f32 v[22:23], v[34:35], v[44:45], v[22:23] op_sel_hi:[1,0,1]
	s_waitcnt lgkmcnt(0)
	v_pk_fma_f32 v[24:25], v[38:39], v[44:45], v[24:25] op_sel_hi:[1,0,1]
	v_pk_fma_f32 v[20:21], v[40:41], v[44:45], v[20:21] op_sel_hi:[1,0,1]
	s_waitcnt vmcnt(14)
	v_lshlrev_b32_e32 v48, 16, v69
	v_pk_fma_f32 v[36:37], v[36:37], v[48:49], v[10:11] op_sel_hi:[1,0,1]
	v_pk_fma_f32 v[34:35], v[34:35], v[48:49], v[14:15] op_sel_hi:[1,0,1]
	v_pk_fma_f32 v[38:39], v[38:39], v[48:49], v[16:17] op_sel_hi:[1,0,1]
	v_pk_fma_f32 v[40:41], v[40:41], v[48:49], v[12:13] op_sel_hi:[1,0,1]
	s_waitcnt vmcnt(13)
	v_lshlrev_b32_e32 v44, 16, v70
	s_waitcnt vmcnt(12)
	v_lshlrev_b32_e32 v48, 16, v71
	ds_read_b128 v[10:13], v1 offset:18432
	ds_read_b128 v[14:17], v1 offset:18448
	s_waitcnt lgkmcnt(1)
	v_pk_fma_f32 v[22:23], v[10:11], v[44:45], v[22:23] op_sel_hi:[1,0,1]
	v_pk_fma_f32 v[34:35], v[10:11], v[48:49], v[34:35] op_sel_hi:[1,0,1]
	s_waitcnt lgkmcnt(0)
	v_pk_fma_f32 v[24:25], v[14:15], v[44:45], v[24:25] op_sel_hi:[1,0,1]
	v_pk_fma_f32 v[18:19], v[12:13], v[44:45], v[18:19] op_sel_hi:[1,0,1]
	v_pk_fma_f32 v[20:21], v[16:17], v[44:45], v[20:21] op_sel_hi:[1,0,1]
	v_pk_fma_f32 v[38:39], v[14:15], v[48:49], v[38:39] op_sel_hi:[1,0,1]
	v_pk_fma_f32 v[36:37], v[12:13], v[48:49], v[36:37] op_sel_hi:[1,0,1]
	v_pk_fma_f32 v[40:41], v[16:17], v[48:49], v[40:41] op_sel_hi:[1,0,1]
	s_waitcnt vmcnt(11)
	v_lshlrev_b32_e32 v44, 16, v72
	s_waitcnt vmcnt(10)
	v_lshlrev_b32_e32 v48, 16, v73
	ds_read_b128 v[10:13], v1 offset:20480
	ds_read_b128 v[14:17], v1 offset:20496
	s_waitcnt lgkmcnt(1)
	v_pk_fma_f32 v[22:23], v[10:11], v[44:45], v[22:23] op_sel_hi:[1,0,1]
	v_pk_fma_f32 v[50:51], v[10:11], v[48:49], v[34:35] op_sel_hi:[1,0,1]
	s_waitcnt lgkmcnt(0)
	v_pk_fma_f32 v[24:25], v[14:15], v[44:45], v[24:25] op_sel_hi:[1,0,1]
	v_pk_fma_f32 v[18:19], v[12:13], v[44:45], v[18:19] op_sel_hi:[1,0,1]
	v_pk_fma_f32 v[20:21], v[16:17], v[44:45], v[20:21] op_sel_hi:[1,0,1]
	v_pk_fma_f32 v[44:45], v[12:13], v[48:49], v[36:37] op_sel_hi:[1,0,1]
	v_pk_fma_f32 v[38:39], v[14:15], v[48:49], v[38:39] op_sel_hi:[1,0,1]
	v_pk_fma_f32 v[40:41], v[16:17], v[48:49], v[40:41] op_sel_hi:[1,0,1]
	s_waitcnt vmcnt(9)
	v_lshlrev_b32_e32 v42, 16, v74
	s_waitcnt vmcnt(8)
	v_lshlrev_b32_e32 v46, 16, v75
	ds_read_b128 v[10:13], v1 offset:22528
	ds_read_b128 v[34:37], v1 offset:22544
	s_waitcnt lgkmcnt(1)
	v_pk_fma_f32 v[22:23], v[10:11], v[42:43], v[22:23] op_sel_hi:[1,0,1]
	s_waitcnt lgkmcnt(0)
; #define LAS __attribute__((address_space(3)))
; DI void gates_phase(LAS unsigned char* lds, const bf16_t* X, const ss_t* ss, const float* win  , const float* ng, const float* gbias, float* GATES, int G, int bid) {
;     ...
;         for (int i = 0; i < 16; ++i) { const int k = lane + 64 * i; const float x0 = __builtin_bit_cast(float, (unsigned)xr0[k] << 16), x1 = __builtin_bit_cast(float, (unsigned)xr1[k] << 16); const f32x4 a = *(const LAS f32x4*)(wg + k * 8), b = *(const LAS f32x4*)(wg + k * 8 + 4);
; #pragma unroll
;             for (int e = 0; e < 4; ++e) { acc[0][e] += x0 * a[e]; acc[0][4 + e] += x0 * b[e]; acc[1][e] += x1 * a[e]; acc[1][4 + e] += x1 * b[e]; } }
; #pragma unroll
;         for (int r = 0; r < 2; ++r) {
;             float v4[4], v2[2], v1;
;             { const bool up = lane & 1;
; #pragma unroll
;               for (int e = 0; e < 4; ++e) { const float keep = up ? acc[r][4 + e] : acc[r][e], send = up ? acc[r][e] : acc[r][4 + e]; v4[e] = keep + __shfl_xor(send, 1); } }
;             { const bool up = lane & 2;
; #pragma unroll
;               for (int e = 0; e < 2; ++e) { const float keep = up ? v4[2 + e] : v4[e], send = up ? v4[e] : v4[2 + e]; v2[e] = keep + __shfl_xor(send, 2); } }
;             { const bool up = lane & 4; const float keep = up ? v2[1] : v2[0], send = up ? v2[0] : v2[1]; v1 = keep + __shfl_xor(send, 4); }
;             v1 += __shfl_xor(v1, 8); v1 += __shfl_xor(v1, 16); v1 += __shfl_xor(v1, 32);
	v_pk_fma_f32 v[24:25], v[34:35], v[42:43], v[24:25] op_sel_hi:[1,0,1]
	v_pk_fma_f32 v[14:15], v[10:11], v[46:47], v[50:51] op_sel_hi:[1,0,1]
	v_pk_fma_f32 v[16:17], v[34:35], v[46:47], v[38:39] op_sel_hi:[1,0,1]
	v_pk_fma_f32 v[18:19], v[12:13], v[42:43], v[18:19] op_sel_hi:[1,0,1]
	v_pk_fma_f32 v[20:21], v[36:37], v[42:43], v[20:21] op_sel_hi:[1,0,1]
	v_pk_fma_f32 v[10:11], v[12:13], v[46:47], v[44:45] op_sel_hi:[1,0,1]
	v_pk_fma_f32 v[12:13], v[36:37], v[46:47], v[40:41] op_sel_hi:[1,0,1]
	s_waitcnt vmcnt(7)
	v_lshlrev_b32_e32 v44, 16, v76
	ds_read_b128 v[34:37], v1 offset:24576
	ds_read_b128 v[38:41], v1 offset:24592
	s_waitcnt lgkmcnt(1)
	v_pk_fma_f32 v[18:19], v[36:37], v[44:45], v[18:19] op_sel_hi:[1,0,1]
	v_pk_fma_f32 v[22:23], v[34:35], v[44:45], v[22:23] op_sel_hi:[1,0,1]
	s_waitcnt lgkmcnt(0)
	v_pk_fma_f32 v[24:25], v[38:39], v[44:45], v[24:25] op_sel_hi:[1,0,1]
	v_pk_fma_f32 v[20:21], v[40:41], v[44:45], v[20:21] op_sel_hi:[1,0,1]
	s_waitcnt vmcnt(6)
	v_lshlrev_b32_e32 v48, 16, v77
	v_pk_fma_f32 v[36:37], v[36:37], v[48:49], v[10:11] op_sel_hi:[1,0,1]
	v_pk_fma_f32 v[34:35], v[34:35], v[48:49], v[14:15] op_sel_hi:[1,0,1]
	v_pk_fma_f32 v[38:39], v[38:39], v[48:49], v[16:17] op_sel_hi:[1,0,1]
	v_pk_fma_f32 v[40:41], v[40:41], v[48:49], v[12:13] op_sel_hi:[1,0,1]
	s_waitcnt vmcnt(5)
	v_lshlrev_b32_e32 v44, 16, v78
	s_waitcnt vmcnt(4)
	v_lshlrev_b32_e32 v48, 16, v79
	ds_read_b128 v[10:13], v1 offset:26624
	ds_read_b128 v[14:17], v1 offset:26640
	s_waitcnt lgkmcnt(1)
	v_pk_fma_f32 v[22:23], v[10:11], v[44:45], v[22:23] op_sel_hi:[1,0,1]
	v_pk_fma_f32 v[34:35], v[10:11], v[48:49], v[34:35] op_sel_hi:[1,0,1]
	s_waitcnt lgkmcnt(0)
	v_pk_fma_f32 v[24:25], v[14:15], v[44:45], v[24:25] op_sel_hi:[1,0,1]
	v_pk_fma_f32 v[18:19], v[12:13], v[44:45], v[18:19] op_sel_hi:[1,0,1]
	v_pk_fma_f32 v[20:21], v[16:17], v[44:45], v[20:21] op_sel_hi:[1,0,1]
	v_pk_fma_f32 v[38:39], v[14:15], v[48:49], v[38:39] op_sel_hi:[1,0,1]
	v_pk_fma_f32 v[36:37], v[12:13], v[48:49], v[36:37] op_sel_hi:[1,0,1]
	v_pk_fma_f32 v[40:41], v[16:17], v[48:49], v[40:41] op_sel_hi:[1,0,1]
	s_waitcnt vmcnt(3)
	v_lshlrev_b32_e32 v44, 16, v80
	s_waitcnt vmcnt(2)
	v_lshlrev_b32_e32 v48, 16, v81
	ds_read_b128 v[10:13], v1 offset:28672
	ds_read_b128 v[14:17], v1 offset:28688
	s_waitcnt lgkmcnt(1)
	v_pk_fma_f32 v[22:23], v[10:11], v[44:45], v[22:23] op_sel_hi:[1,0,1]
	v_pk_fma_f32 v[50:51], v[10:11], v[48:49], v[34:35] op_sel_hi:[1,0,1]
	s_waitcnt lgkmcnt(0)
	v_pk_fma_f32 v[24:25], v[14:15], v[44:45], v[24:25] op_sel_hi:[1,0,1]
	v_pk_fma_f32 v[18:19], v[12:13], v[44:45], v[18:19] op_sel_hi:[1,0,1]
	v_pk_fma_f32 v[20:21], v[16:17], v[44:45], v[20:21] op_sel_hi:[1,0,1]
	v_pk_fma_f32 v[44:45], v[12:13], v[48:49], v[36:37] op_sel_hi:[1,0,1]
	v_pk_fma_f32 v[38:39], v[14:15], v[48:49], v[38:39] op_sel_hi:[1,0,1]
	v_pk_fma_f32 v[40:41], v[16:17], v[48:49], v[40:41] op_sel_hi:[1,0,1]
	s_waitcnt vmcnt(1)
	v_lshlrev_b32_e32 v42, 16, v82
	s_waitcnt vmcnt(0)
	v_lshlrev_b32_e32 v46, 16, v83
	ds_read_b128 v[10:13], v1 offset:30720
	ds_read_b128 v[34:37], v1 offset:30736
	s_waitcnt lgkmcnt(1)
	v_pk_fma_f32 v[22:23], v[10:11], v[42:43], v[22:23] op_sel_hi:[1,0,1]
	s_waitcnt lgkmcnt(0)
	v_pk_fma_f32 v[24:25], v[34:35], v[42:43], v[24:25] op_sel_hi:[1,0,1]
	v_pk_fma_f32 v[14:15], v[10:11], v[46:47], v[50:51] op_sel_hi:[1,0,1]
	v_pk_fma_f32 v[16:17], v[34:35], v[46:47], v[38:39] op_sel_hi:[1,0,1]
	v_pk_fma_f32 v[18:19], v[12:13], v[42:43], v[18:19] op_sel_hi:[1,0,1]
	v_pk_fma_f32 v[20:21], v[36:37], v[42:43], v[20:21] op_sel_hi:[1,0,1]
	v_pk_fma_f32 v[10:11], v[12:13], v[46:47], v[44:45] op_sel_hi:[1,0,1]
	v_pk_fma_f32 v[12:13], v[36:37], v[46:47], v[40:41] op_sel_hi:[1,0,1]
	v_cndmask_b32_e32 v33, v24, v22, vcc
	v_cndmask_b32_e32 v22, v22, v24, vcc
	v_cndmask_b32_e32 v24, v25, v23, vcc
	v_cndmask_b32_e32 v23, v23, v25, vcc
	ds_bpermute_b32 v23, v26, v23
	ds_bpermute_b32 v22, v26, v22
	v_ashrrev_i32_e32 v1, 31, v0
	s_waitcnt lgkmcnt(1)
	v_add_f32_e32 v23, v24, v23
	v_cndmask_b32_e32 v24, v20, v18, vcc
	v_cndmask_b32_e32 v18, v18, v20, vcc
	ds_bpermute_b32 v18, v26, v18
	v_cndmask_b32_e32 v20, v21, v19, vcc
	v_cndmask_b32_e32 v19, v19, v21, vcc
	ds_bpermute_b32 v19, v26, v19
	s_waitcnt lgkmcnt(2)
	v_add_f32_e32 v22, v33, v22
	s_waitcnt lgkmcnt(1)
	v_add_f32_e32 v18, v24, v18
	s_waitcnt lgkmcnt(0)
	v_add_f32_e32 v19, v20, v19
	v_cndmask_b32_e64 v20, v18, v22, s[38:39]
	v_cndmask_b32_e64 v18, v22, v18, s[38:39]
	ds_bpermute_b32 v18, v27, v18
	s_waitcnt lgkmcnt(0)
	v_add_f32_e32 v18, v20, v18
	v_cndmask_b32_e64 v20, v19, v23, s[38:39]
	v_cndmask_b32_e64 v19, v23, v19, s[38:39]
	ds_bpermute_b32 v19, v27, v19
	s_waitcnt lgkmcnt(0)
	v_add_f32_e32 v19, v20, v19
	v_cndmask_b32_e64 v20, v19, v18, s[40:41]
	v_cndmask_b32_e64 v18, v18, v19, s[40:41]
	ds_bpermute_b32 v18, v28, v18
	s_waitcnt lgkmcnt(0)
	v_add_f32_e32 v18, v20, v18
	ds_bpermute_b32 v19, v29, v18
	s_waitcnt lgkmcnt(0)
	v_add_f32_e32 v18, v18, v19
	ds_bpermute_b32 v19, v30, v18
	s_waitcnt lgkmcnt(0)
	v_add_f32_e32 v18, v18, v19
	ds_bpermute_b32 v19, v31, v18
	s_and_saveexec_b64 s[52:53], s[42:43]
	s_cbranch_execz .LBB0_451
; DI float frsq(float x) { return __builtin_amdgcn_rsqf(x); }
; DI float ss_get(const ss_t* ss, int r) { return (float)ss[r] * (1.0f / 1048576.0f); }
; DI void gates_phase(LAS unsigned char* lds, const bf16_t* X, const ss_t* ss, const float* win  , const float* ng, const float* gbias, float* GATES, int G, int bid) {
;     ...
;             const int m = m0 + r * NGW;
;             const float rs = frsq(ss_get(ss, m) * (1.0f / 1024.0f) + EPS);
;             if (lane < 8) { const int j = (lane & 1) * 4 + ((lane >> 1) & 1) * 2 + ((lane >> 2) & 1);
;                 float v = v1 * rs + gbias[j];
;                 if (j >= 4) v = fminf(v, 0.f) - log1pf(expf(-fabsf(v)));
;                 GATES[(size_t)m * 8 + j] = v; }
	v_mov_b32_e32 v20, v84
	v_mov_b32_e32 v21, v85
	s_waitcnt lgkmcnt(0)
	v_add_f32_e32 v19, v18, v19
	v_mov_b32_e32 v18, v88
	v_xor_b32_e32 v22, v20, v21
	v_ashrrev_i32_e32 v22, 31, v22
	v_ffbh_i32_e32 v23, v21
	v_add_u32_e32 v22, 32, v22
	v_add_u32_e32 v23, -1, v23
	v_min_u32_e32 v22, v23, v22
	v_lshlrev_b64 v[20:21], v22, v[20:21]
	v_min_u32_e32 v20, 1, v20
	v_or_b32_e32 v20, v21, v20
	v_cvt_f32_i32_e32 v20, v20
	v_sub_u32_e32 v21, 32, v22
	v_ldexp_f32 v20, v20, v21
	v_mul_f32_e32 v20, 0x35800000, v20
	v_fmamk_f32 v20, v20, 0x3a800000, v229
	v_rsq_f32_e32 v20, v20
	s_nop 0
	v_fmac_f32_e32 v18, v19, v20
	s_and_saveexec_b64 s[54:55], s[44:45]
	s_cbranch_execz .LBB0_450
	s_mov_b32 s0, 0xbfb8aa3b
	v_mul_f32_e64 v19, |v18|, s0
	v_rndne_f32_e32 v20, v19
	v_sub_f32_e32 v21, v19, v20
	v_fma_f32 v19, |v18|, s0, -v19
	s_mov_b32 s0, 0xb2a5705f
	v_fma_f32 v19, |v18|, s0, v19
	v_add_f32_e32 v19, v21, v19
	v_exp_f32_e32 v19, v19
	v_cvt_i32_f32_e32 v20, v20
	s_mov_b32 s0, 0x42ce8ed0
	v_cmp_ngt_f32_e64 s[0:1], |v18|, s0
	v_max_f32_e32 v21, v18, v18
	v_ldexp_f32 v19, v19, v20
	v_cndmask_b32_e64 v19, 0, v19, s[0:1]
	s_mov_b32 s0, 0xc2b17218
	v_cmp_nlt_f32_e64 s[0:1], |v18|, s0
	v_min_f32_e32 v33, 0, v21
	s_nop 0
	v_cndmask_b32_e64 v40, v236, v19, s[0:1]
	v_add_f32_e32 v20, 1.0, v40
	v_add_f32_e32 v18, -1.0, v20
	v_sub_f32_e32 v19, v18, v20
	v_add_f32_e32 v19, 1.0, v19
	v_sub_f32_e32 v18, v40, v18
	v_add_f32_e32 v21, v18, v19
	v_frexp_mant_f32_e32 v22, v20
	v_cvt_f64_f32_e32 v[18:19], v20
	s_mov_b32 s0, 0x3f2aaaab
	v_frexp_exp_i32_f64_e32 v18, v[18:19]
	v_cmp_gt_f32_e64 s[0:1], s0, v22
	s_nop 1
	v_subbrev_co_u32_e64 v34, s[0:1], 0, v18, s[0:1]
	v_sub_u32_e32 v18, 0, v34
	v_ldexp_f32 v19, v20, v18
	v_add_f32_e32 v20, -1.0, v19
	v_add_f32_e32 v22, 1.0, v19
	v_ldexp_f32 v18, v21, v18
	v_add_f32_e32 v21, 1.0, v20
	v_add_f32_e32 v23, -1.0, v22
	v_sub_f32_e32 v21, v19, v21
	v_sub_f32_e32 v19, v19, v23
	v_add_f32_e32 v21, v18, v21
	v_add_f32_e32 v18, v18, v19
	v_add_f32_e32 v35, v22, v18
	v_rcp_f32_e32 v37, v35
	v_sub_f32_e32 v19, v22, v35
	v_add_f32_e32 v36, v18, v19
	v_add_f32_e32 v19, v20, v21
	v_mul_f32_e32 v39, v19, v37
	v_sub_f32_e32 v18, v20, v19
	v_mul_f32_e32 v20, v35, v39
	v_fma_f32 v22, v39, v35, -v20
	v_fmac_f32_e32 v22, v39, v36
	v_add_f32_e32 v38, v21, v18
	v_add_f32_e32 v18, v20, v22
	v_sub_f32_e32 v21, v19, v18
	v_pk_add_f32 v[24:25], v[18:19], v[20:21] neg_lo:[0,1] neg_hi:[0,1]
	v_mov_b32_e32 v23, v18
	v_pk_add_f32 v[18:19], v[24:25], v[22:23] neg_lo:[0,1] neg_hi:[0,1]
	s_mov_b32 s0, 0x3f317218
	v_add_f32_e32 v19, v38, v19
	v_add_f32_e32 v18, v18, v19
	v_add_f32_e32 v19, v21, v18
	v_mul_f32_e32 v38, v37, v19
	v_mul_f32_e32 v20, v35, v38
	v_fma_f32 v22, v38, v35, -v20
	v_fmac_f32_e32 v22, v38, v36
	v_sub_f32_e32 v21, v21, v19
	v_add_f32_e32 v35, v18, v21
	v_add_f32_e32 v18, v20, v22
	v_sub_f32_e32 v21, v19, v18
	v_pk_add_f32 v[24:25], v[18:19], v[20:21] neg_lo:[0,1] neg_hi:[0,1]
	v_mov_b32_e32 v23, v18
	v_pk_add_f32 v[18:19], v[24:25], v[22:23] neg_lo:[0,1] neg_hi:[0,1]
	s_nop 0
	v_add_f32_e32 v19, v35, v19
	v_add_f32_e32 v18, v18, v19
	v_add_f32_e32 v19, v39, v38
	v_add_f32_e32 v18, v21, v18
	v_sub_f32_e32 v20, v19, v39
	v_mul_f32_e32 v18, v37, v18
	v_sub_f32_e32 v20, v38, v20
	v_add_f32_e32 v20, v20, v18
	v_add_f32_e32 v22, v19, v20
	v_mul_f32_e32 v23, v22, v22
	v_fmamk_f32 v18, v23, 0x3e9b6dac, v230
	v_fmaak_f32 v191, v23, v18, 0x3f2aaada
	v_cvt_f32_i32_e32 v18, v34
	v_sub_f32_e32 v19, v22, v19
	v_sub_f32_e32 v19, v20, v19
	v_ldexp_f32 v24, v19, 1
	v_mul_f32_e32 v19, v22, v23
	v_ldexp_f32 v21, v22, 1
	v_pk_mul_f32 v[22:23], v[18:19], v[190:191]
	s_nop 0
	v_fma_f32 v20, v18, s0, -v22
	v_fmac_f32_e32 v20, 0xb102e308, v18
	v_pk_add_f32 v[18:19], v[22:23], v[20:21]
	s_mov_b32 s0, 0x7f800000
	v_sub_f32_e32 v21, v19, v21
	v_sub_f32_e32 v21, v23, v21
	v_add_f32_e32 v25, v24, v21
	v_mov_b32_e32 v24, v22
	v_pk_add_f32 v[22:23], v[18:19], v[22:23] neg_lo:[0,1] neg_hi:[0,1]
	v_pk_add_f32 v[34:35], v[18:19], v[24:25]
	v_mov_b32_e32 v21, v18
	v_mov_b32_e32 v23, v35
	v_pk_add_f32 v[36:37], v[20:21], v[22:23] neg_lo:[0,1] neg_hi:[0,1]
	v_pk_add_f32 v[20:21], v[20:21], v[22:23]
	v_mov_b32_e32 v24, v25
	v_pk_add_f32 v[22:23], v[20:21], v[18:19] op_sel:[1,0] op_sel_hi:[0,1] neg_lo:[0,1] neg_hi:[0,1]
	v_pk_add_f32 v[38:39], v[34:35], v[22:23] op_sel_hi:[1,0] neg_lo:[0,1] neg_hi:[0,1]
	v_mov_b32_e32 v34, v35
	v_mov_b32_e32 v35, v21
	v_pk_mov_b32 v[22:23], v[18:19], v[22:23] op_sel:[1,0]
	v_mov_b32_e32 v25, v18
	v_pk_add_f32 v[22:23], v[34:35], v[22:23] neg_lo:[0,1] neg_hi:[0,1]
	v_mov_b32_e32 v38, v36
	v_pk_add_f32 v[18:19], v[24:25], v[22:23] neg_lo:[0,1] neg_hi:[0,1]
	v_mov_b32_e32 v37, v21
	v_pk_add_f32 v[22:23], v[38:39], v[18:19]
	v_cmp_neq_f32_e64 s[0:1], s0, v40
	v_pk_add_f32 v[24:25], v[22:23], v[22:23] op_sel:[0,1] op_sel_hi:[1,0]
	s_nop 0
	v_pk_add_f32 v[20:21], v[20:21], v[24:25] op_sel:[1,0] op_sel_hi:[0,1]
	v_mov_b32_e32 v23, v20
	v_pk_add_f32 v[34:35], v[22:23], v[36:37] neg_lo:[0,1] neg_hi:[0,1]
	v_mov_b32_e32 v19, v24
	v_sub_f32_e32 v21, v22, v34
	v_pk_add_f32 v[18:19], v[18:19], v[34:35] neg_lo:[0,1] neg_hi:[0,1]
	v_sub_f32_e32 v21, v36, v21
	v_add_f32_e32 v18, v18, v21
	v_add_f32_e32 v18, v18, v19
	v_add_f32_e32 v18, v20, v18
	v_cndmask_b32_e64 v18, v236, v18, s[0:1]
	s_mov_b32 s0, 0x33800000
	v_cmp_lt_f32_e64 s[0:1], |v40|, s0
	s_nop 1
	v_cndmask_b32_e64 v18, v18, v40, s[0:1]
	v_sub_f32_e32 v18, v33, v18

; DI float frsq(float x) { return __builtin_amdgcn_rsqf(x); }
; DI float ss_get(const ss_t* ss, int r) { return (float)ss[r] * (1.0f / 1048576.0f); }
; DI void gates_phase(LAS unsigned char* lds, const bf16_t* X, const ss_t* ss, const float* win  , const float* ng, const float* gbias, float* GATES, int G, int bid) {
;     ...
;         for (int r = 0; r < 2; ++r) {
;             float v4[4], v2[2], v1;
;             { const bool up = lane & 1;
; #pragma unroll
;               for (int e = 0; e < 4; ++e) { const float keep = up ? acc[r][4 + e] : acc[r][e], send = up ? acc[r][e] : acc[r][4 + e]; v4[e] = keep + __shfl_xor(send, 1); } }
;             { const bool up = lane & 2;
; #pragma unroll
;               for (int e = 0; e < 2; ++e) { const float keep = up ? v4[2 + e] : v4[e], send = up ? v4[e] : v4[2 + e]; v2[e] = keep + __shfl_xor(send, 2); } }
;             { const bool up = lane & 4; const float keep = up ? v2[1] : v2[0], send = up ? v2[0] : v2[1]; v1 = keep + __shfl_xor(send, 4); }
;             v1 += __shfl_xor(v1, 8); v1 += __shfl_xor(v1, 16); v1 += __shfl_xor(v1, 32);
;             const int m = m0 + r * NGW;
;             const float rs = frsq(ss_get(ss, m) * (1.0f / 1024.0f) + EPS);
;             if (lane < 8) { const int j = (lane & 1) * 4 + ((lane >> 1) & 1) * 2 + ((lane >> 2) & 1);
;                 float v = v1 * rs + gbias[j];
;                 if (j >= 4) v = fminf(v, 0.f) - log1pf(expf(-fabsf(v)));
;                 GATES[(size_t)m * 8 + j] = v; }
.LBB0_451:
	s_or_b64 exec, exec, s[52:53]
	v_cndmask_b32_e32 v1, v14, v16, vcc
	ds_bpermute_b32 v1, v26, v1
	v_cndmask_b32_e32 v14, v16, v14, vcc
	v_cndmask_b32_e32 v16, v17, v15, vcc
	v_cndmask_b32_e32 v15, v15, v17, vcc
	v_cndmask_b32_e32 v17, v11, v13, vcc
	s_waitcnt lgkmcnt(0)
	v_add_f32_e32 v1, v14, v1
	v_cndmask_b32_e32 v14, v10, v12, vcc
	ds_bpermute_b32 v15, v26, v15
	ds_bpermute_b32 v14, v26, v14
	ds_bpermute_b32 v17, v26, v17
	v_cndmask_b32_e32 v10, v12, v10, vcc
	v_cndmask_b32_e32 v11, v13, v11, vcc
	s_waitcnt lgkmcnt(2)
	v_add_f32_e32 v15, v16, v15
	s_waitcnt lgkmcnt(1)
	v_add_f32_e32 v10, v10, v14
	s_waitcnt lgkmcnt(0)
	v_add_f32_e32 v11, v11, v17
	v_cndmask_b32_e64 v12, v1, v10, s[38:39]
	v_cndmask_b32_e64 v13, v15, v11, s[38:39]
	ds_bpermute_b32 v12, v27, v12
	ds_bpermute_b32 v13, v27, v13
	v_cndmask_b32_e64 v1, v10, v1, s[38:39]
	v_cndmask_b32_e64 v10, v11, v15, s[38:39]
	s_waitcnt lgkmcnt(1)
	v_add_f32_e32 v1, v1, v12
	s_waitcnt lgkmcnt(0)
	v_add_f32_e32 v10, v10, v13
	v_cndmask_b32_e64 v11, v1, v10, s[40:41]
	ds_bpermute_b32 v11, v28, v11
	v_cndmask_b32_e64 v1, v10, v1, s[40:41]
	s_waitcnt lgkmcnt(0)
	v_add_f32_e32 v1, v1, v11
	ds_bpermute_b32 v10, v29, v1
	s_waitcnt lgkmcnt(0)
	v_add_f32_e32 v1, v1, v10
	ds_bpermute_b32 v10, v30, v1
	s_waitcnt lgkmcnt(0)
	v_add_f32_e32 v1, v1, v10
	ds_bpermute_b32 v12, v31, v1
	s_and_saveexec_b64 s[52:53], s[42:43]
	s_cbranch_execz .LBB0_444
	v_add_u32_e32 v10, s33, v0
	v_ashrrev_i32_e32 v11, 31, v10
	v_mov_b32_e32 v14, v86
	v_mov_b32_e32 v15, v87
	s_waitcnt lgkmcnt(0)
	v_add_f32_e32 v12, v1, v12
	v_mov_b32_e32 v1, v88
	v_xor_b32_e32 v13, v14, v15
	v_ashrrev_i32_e32 v13, 31, v13
	v_ffbh_i32_e32 v16, v15
	v_add_u32_e32 v13, 32, v13
	v_add_u32_e32 v16, -1, v16
	v_min_u32_e32 v13, v16, v13
	v_lshlrev_b64 v[14:15], v13, v[14:15]
	v_min_u32_e32 v14, 1, v14
	v_or_b32_e32 v14, v15, v14
	v_cvt_f32_i32_e32 v14, v14
	v_sub_u32_e32 v13, 32, v13
	v_ldexp_f32 v13, v14, v13
	v_mul_f32_e32 v13, 0x35800000, v13
	v_fmamk_f32 v13, v13, 0x3a800000, v229
	v_rsq_f32_e32 v13, v13
	s_nop 0
	v_fmac_f32_e32 v1, v12, v13
	s_and_saveexec_b64 s[54:55], s[44:45]
	s_cbranch_execz .LBB0_443
	s_mov_b32 s0, 0xbfb8aa3b
	v_mul_f32_e64 v12, |v1|, s0
	v_rndne_f32_e32 v13, v12
	v_sub_f32_e32 v14, v12, v13
	v_fma_f32 v12, |v1|, s0, -v12
	s_mov_b32 s0, 0xb2a5705f
	v_fma_f32 v12, |v1|, s0, v12
	v_add_f32_e32 v12, v14, v12
	v_exp_f32_e32 v12, v12
	v_cvt_i32_f32_e32 v13, v13
	s_mov_b32 s0, 0x42ce8ed0
	v_cmp_ngt_f32_e64 s[0:1], |v1|, s0
	v_max_f32_e32 v14, v1, v1
	v_ldexp_f32 v12, v12, v13
	v_cndmask_b32_e64 v12, 0, v12, s[0:1]
	s_mov_b32 s0, 0xc2b17218
	v_cmp_nlt_f32_e64 s[0:1], |v1|, s0
	v_min_f32_e32 v33, 0, v14
	s_nop 0
	v_cndmask_b32_e64 v1, v236, v12, s[0:1]
	v_add_f32_e32 v14, 1.0, v1
	v_add_f32_e32 v12, -1.0, v14
	v_sub_f32_e32 v13, v12, v14
	v_add_f32_e32 v13, 1.0, v13
	v_sub_f32_e32 v12, v1, v12
	v_add_f32_e32 v15, v12, v13
	v_frexp_mant_f32_e32 v16, v14
	v_cvt_f64_f32_e32 v[12:13], v14
	s_mov_b32 s0, 0x3f2aaaab
	v_frexp_exp_i32_f64_e32 v12, v[12:13]
	v_cmp_gt_f32_e64 s[0:1], s0, v16
	s_nop 1
	v_subbrev_co_u32_e64 v20, s[0:1], 0, v12, s[0:1]
	v_sub_u32_e32 v12, 0, v20
	v_ldexp_f32 v13, v14, v12
	v_add_f32_e32 v14, -1.0, v13
	v_add_f32_e32 v16, 1.0, v13
	v_ldexp_f32 v12, v15, v12
	v_add_f32_e32 v15, 1.0, v14
	v_add_f32_e32 v17, -1.0, v16
	v_sub_f32_e32 v15, v13, v15
	v_sub_f32_e32 v13, v13, v17
	v_add_f32_e32 v15, v12, v15
	v_add_f32_e32 v12, v12, v13
	v_add_f32_e32 v21, v16, v12
	v_rcp_f32_e32 v23, v21
	v_sub_f32_e32 v13, v16, v21
	v_add_f32_e32 v22, v12, v13
	v_add_f32_e32 v13, v14, v15
	v_mul_f32_e32 v25, v13, v23
	v_sub_f32_e32 v12, v14, v13
	v_mul_f32_e32 v14, v21, v25
	v_fma_f32 v16, v25, v21, -v14
	v_fmac_f32_e32 v16, v25, v22
	v_add_f32_e32 v24, v15, v12
	v_add_f32_e32 v12, v14, v16
	v_sub_f32_e32 v15, v13, v12
	v_pk_add_f32 v[18:19], v[12:13], v[14:15] neg_lo:[0,1] neg_hi:[0,1]
	v_mov_b32_e32 v17, v12
	v_pk_add_f32 v[12:13], v[18:19], v[16:17] neg_lo:[0,1] neg_hi:[0,1]
	s_mov_b32 s0, 0x3f317218
	v_add_f32_e32 v13, v24, v13
	v_add_f32_e32 v12, v12, v13
	v_add_f32_e32 v13, v15, v12
	v_mul_f32_e32 v24, v23, v13
	v_mul_f32_e32 v14, v21, v24
	v_fma_f32 v16, v24, v21, -v14
	v_fmac_f32_e32 v16, v24, v22
	v_sub_f32_e32 v15, v15, v13
	v_add_f32_e32 v21, v12, v15
	v_add_f32_e32 v12, v14, v16
	v_sub_f32_e32 v15, v13, v12
	v_pk_add_f32 v[18:19], v[12:13], v[14:15] neg_lo:[0,1] neg_hi:[0,1]
	v_mov_b32_e32 v17, v12
	v_pk_add_f32 v[12:13], v[18:19], v[16:17] neg_lo:[0,1] neg_hi:[0,1]
	s_nop 0
	v_add_f32_e32 v13, v21, v13
	v_add_f32_e32 v12, v12, v13
	v_add_f32_e32 v13, v25, v24
	v_add_f32_e32 v12, v15, v12
	v_sub_f32_e32 v14, v13, v25
	v_mul_f32_e32 v12, v23, v12
	v_sub_f32_e32 v14, v24, v14
	v_add_f32_e32 v14, v14, v12
	v_add_f32_e32 v16, v13, v14
	v_mul_f32_e32 v17, v16, v16
	v_fmamk_f32 v12, v17, 0x3e9b6dac, v230
	v_fmaak_f32 v191, v17, v12, 0x3f2aaada
	v_cvt_f32_i32_e32 v12, v20
	v_sub_f32_e32 v13, v16, v13
	v_sub_f32_e32 v13, v14, v13
	v_ldexp_f32 v18, v13, 1
	v_mul_f32_e32 v13, v16, v17
	v_ldexp_f32 v15, v16, 1
	v_pk_mul_f32 v[16:17], v[12:13], v[190:191]
	s_nop 0
	v_fma_f32 v14, v12, s0, -v16
	v_fmac_f32_e32 v14, 0xb102e308, v12
	v_pk_add_f32 v[12:13], v[16:17], v[14:15]
	s_mov_b32 s0, 0x7f800000
	v_sub_f32_e32 v15, v13, v15
	v_sub_f32_e32 v15, v17, v15
	v_add_f32_e32 v19, v18, v15
	v_mov_b32_e32 v18, v16
	v_pk_add_f32 v[16:17], v[12:13], v[16:17] neg_lo:[0,1] neg_hi:[0,1]
	v_pk_add_f32 v[20:21], v[12:13], v[18:19]
	v_mov_b32_e32 v15, v12
	v_mov_b32_e32 v17, v21
	v_pk_add_f32 v[22:23], v[14:15], v[16:17] neg_lo:[0,1] neg_hi:[0,1]
	v_pk_add_f32 v[14:15], v[14:15], v[16:17]
	v_mov_b32_e32 v18, v19
	v_pk_add_f32 v[16:17], v[14:15], v[12:13] op_sel:[1,0] op_sel_hi:[0,1] neg_lo:[0,1] neg_hi:[0,1]
	v_pk_add_f32 v[24:25], v[20:21], v[16:17] op_sel_hi:[1,0] neg_lo:[0,1] neg_hi:[0,1]
	v_mov_b32_e32 v20, v21
	v_mov_b32_e32 v21, v15
	v_pk_mov_b32 v[16:17], v[12:13], v[16:17] op_sel:[1,0]
	v_mov_b32_e32 v19, v12
	v_pk_add_f32 v[16:17], v[20:21], v[16:17] neg_lo:[0,1] neg_hi:[0,1]
	v_mov_b32_e32 v24, v22
	v_pk_add_f32 v[12:13], v[18:19], v[16:17] neg_lo:[0,1] neg_hi:[0,1]
	v_mov_b32_e32 v23, v15
	v_pk_add_f32 v[16:17], v[24:25], v[12:13]
	v_cmp_neq_f32_e64 s[0:1], s0, v1
	v_pk_add_f32 v[18:19], v[16:17], v[16:17] op_sel:[0,1] op_sel_hi:[1,0]
	s_nop 0
	v_pk_add_f32 v[14:15], v[14:15], v[18:19] op_sel:[1,0] op_sel_hi:[0,1]
	v_mov_b32_e32 v17, v14
	v_pk_add_f32 v[20:21], v[16:17], v[22:23] neg_lo:[0,1] neg_hi:[0,1]
	v_mov_b32_e32 v13, v18
	v_sub_f32_e32 v15, v16, v20
	v_pk_add_f32 v[12:13], v[12:13], v[20:21] neg_lo:[0,1] neg_hi:[0,1]
	v_sub_f32_e32 v15, v22, v15
	v_add_f32_e32 v12, v12, v15
	v_add_f32_e32 v12, v12, v13
	v_add_f32_e32 v12, v14, v12
	v_cndmask_b32_e64 v12, v236, v12, s[0:1]
	s_mov_b32 s0, 0x33800000
	v_cmp_lt_f32_e64 s[0:1], |v1|, s0
	s_nop 1
	v_cndmask_b32_e64 v1, v12, v1, s[0:1]
	v_sub_f32_e32 v1, v33, v1
	s_branch .LBB0_443
